# grid barrier: the L1 invalidate is issued before polling the arrival counter (the CU issues no loads between it and the release), so it overlaps the wait
# speedup vs baseline: 1.0223x; 1.0105x over previous
.LBB0_331:
	s_waitcnt vmcnt(0)
	s_waitcnt lgkmcnt(0)
	s_barrier
	s_mov_b64 s[4:5], exec
	v_readlane_b32 s0, v126, 10
	v_readlane_b32 s1, v126, 11
	s_and_b64 s[0:1], s[4:5], s[0:1]
	s_mov_b64 exec, s[0:1]
	s_cbranch_execz .LBB0_383
	v_readlane_b32 s8, v126, 12
	v_readlane_b32 s9, v126, 13
	v_readlane_b32 s3, v126, 14
	v_mov_b32_e32 v0, 0
	v_mov_b32_e32 v1, 1
	s_lshl_b32 s3, s3, 8
	s_add_u32 s0, s8, s3
	s_addc_u32 s1, s9, 0
	s_add_u32 s0, s0, 0x1400
	s_addc_u32 s1, s1, 0
	global_atomic_add v4, v0, v1, s[0:1] sc0
	v_mov_b32_e32 v5, 0x23ff0
	ds_read2_b32 v[2:3], v5 offset1:1
	s_add_u32 s8, s8, 0x3400
	s_addc_u32 s9, s9, 0
	s_sub_i32 s3, 3, s90
	s_mov_b32 s7, 0
	s_waitcnt lgkmcnt(0)
	v_readfirstlane_b32 s1, v2
	v_readfirstlane_b32 s6, v3
	s_mul_i32 s1, s1, s3
	s_mul_i32 s6, s6, s3
	s_waitcnt vmcnt(0)
	v_readfirstlane_b32 s0, v4
	s_add_i32 s0, s0, 1
	s_cmp_lg_u32 s0, s1
	s_cbranch_scc1 .Lgb2_inv
	buffer_wbl2 sc1
	s_waitcnt vmcnt(0)
	global_atomic_add v0, v1, s[8:9]
.Lgb2_inv:
	buffer_inv sc1
.Lgb2_poll:
	global_load_dword v4, v0, s[8:9] sc1
	s_waitcnt vmcnt(0)
	v_readfirstlane_b32 s0, v4
	s_sub_i32 s0, s0, s6
	s_cmp_ge_i32 s0, 0
	s_cbranch_scc1 .Lgb2_rel
	s_add_i32 s7, s7, 1
	s_sleep 1
	s_cmp_lt_u32 s7, 0x2000
	s_cbranch_scc1 .Lgb2_poll
.Lgb2_rel:
.LBB0_383:
	s_or_b64 exec, exec, s[4:5]
	s_waitcnt lgkmcnt(0)
	s_barrier

.LBB0_535:
	s_cmp_lt_i32 s91, 5
	s_cbranch_scc1 .LBB0_589
	s_waitcnt vmcnt(0)
	s_waitcnt lgkmcnt(0)
	s_barrier
	s_mov_b64 s[4:5], exec
	v_readlane_b32 s0, v126, 10
	v_readlane_b32 s1, v126, 11
	s_and_b64 s[0:1], s[4:5], s[0:1]
	s_mov_b64 exec, s[0:1]
	s_cbranch_execz .LBB0_588
	v_readlane_b32 s8, v126, 12
	v_readlane_b32 s9, v126, 13
	v_readlane_b32 s3, v126, 14
	v_mov_b32_e32 v0, 0
	v_mov_b32_e32 v1, 1
	s_lshl_b32 s3, s3, 8
	s_add_u32 s0, s8, s3
	s_addc_u32 s1, s9, 0
	s_add_u32 s0, s0, 0x1400
	s_addc_u32 s1, s1, 0
	global_atomic_add v4, v0, v1, s[0:1] sc0
	v_mov_b32_e32 v5, 0x23ff0
	ds_read2_b32 v[2:3], v5 offset1:1
	s_add_u32 s8, s8, 0x3400
	s_addc_u32 s9, s9, 0
	s_sub_i32 s3, 4, s90
	s_mov_b32 s7, 0
	s_waitcnt lgkmcnt(0)
	v_readfirstlane_b32 s1, v2
	v_readfirstlane_b32 s6, v3
	s_mul_i32 s1, s1, s3
	s_mul_i32 s6, s6, s3
	s_waitcnt vmcnt(0)
	v_readfirstlane_b32 s0, v4
	s_add_i32 s0, s0, 1
	s_cmp_lg_u32 s0, s1
	s_cbranch_scc1 .Lgb3_inv
	buffer_wbl2 sc1
	s_waitcnt vmcnt(0)
	global_atomic_add v0, v1, s[8:9]
.Lgb3_inv:
	buffer_inv sc1
.Lgb3_poll:
	global_load_dword v4, v0, s[8:9] sc1
	s_waitcnt vmcnt(0)
	v_readfirstlane_b32 s0, v4
	s_sub_i32 s0, s0, s6
	s_cmp_ge_i32 s0, 0
	s_cbranch_scc1 .Lgb3_rel
	s_add_i32 s7, s7, 1
	s_sleep 1
	s_cmp_lt_u32 s7, 0x2000
	s_cbranch_scc1 .Lgb3_poll

.LBB0_611:
	s_cmp_lt_i32 s91, 6
	s_cbranch_scc1 .LBB0_665
	s_waitcnt vmcnt(0)
	s_waitcnt lgkmcnt(0)
	s_barrier
	s_mov_b64 s[6:7], exec
	v_readlane_b32 s0, v126, 10
	v_readlane_b32 s1, v126, 11
	s_and_b64 s[0:1], s[6:7], s[0:1]
	s_mov_b64 exec, s[0:1]
	s_cbranch_execz .LBB0_664
	v_readlane_b32 s8, v126, 12
	v_readlane_b32 s9, v126, 13
	v_readlane_b32 s3, v126, 14
	v_mov_b32_e32 v0, 0
	v_mov_b32_e32 v1, 1
	s_lshl_b32 s3, s3, 8
	s_add_u32 s0, s8, s3
	s_addc_u32 s1, s9, 0
	s_add_u32 s0, s0, 0x1400
	s_addc_u32 s1, s1, 0
	global_atomic_add v4, v0, v1, s[0:1] sc0
	v_mov_b32_e32 v5, 0x23ff0
	ds_read2_b32 v[2:3], v5 offset1:1
	s_add_u32 s8, s8, 0x3400
	s_addc_u32 s9, s9, 0
	s_sub_i32 s3, 5, s90
	s_mov_b32 s5, 0
	s_waitcnt lgkmcnt(0)
	v_readfirstlane_b32 s1, v2
	v_readfirstlane_b32 s4, v3
	s_mul_i32 s1, s1, s3
	s_mul_i32 s4, s4, s3
	s_waitcnt vmcnt(0)
	v_readfirstlane_b32 s0, v4
	s_add_i32 s0, s0, 1
	s_cmp_lg_u32 s0, s1
	s_cbranch_scc1 .Lgb4_inv
	buffer_wbl2 sc1
	s_waitcnt vmcnt(0)
	global_atomic_add v0, v1, s[8:9]
.Lgb4_inv:
	buffer_inv sc1
.Lgb4_poll:
	global_load_dword v4, v0, s[8:9] sc1
	s_waitcnt vmcnt(0)
	v_readfirstlane_b32 s0, v4
	s_sub_i32 s0, s0, s4
	s_cmp_ge_i32 s0, 0
	s_cbranch_scc1 .Lgb4_rel
	s_add_i32 s5, s5, 1
	s_sleep 1
	s_cmp_lt_u32 s5, 0x2000
	s_cbranch_scc1 .Lgb4_poll
.Lgb4_rel:
.LBB0_664:
	s_or_b64 exec, exec, s[6:7]
	s_waitcnt lgkmcnt(0)
	s_barrier

.LBB0_690:
	s_cmp_lt_i32 s91, 7
	s_cbranch_scc1 .LBB0_744
	s_waitcnt vmcnt(0)
	s_waitcnt lgkmcnt(0)
	s_barrier
	s_mov_b64 s[4:5], exec
	v_readlane_b32 s0, v126, 10
	v_readlane_b32 s1, v126, 11
	s_and_b64 s[0:1], s[4:5], s[0:1]
	s_mov_b64 exec, s[0:1]
	s_cbranch_execz .LBB0_743
	v_readlane_b32 s8, v126, 12
	v_readlane_b32 s9, v126, 13
	v_readlane_b32 s3, v126, 14
	v_mov_b32_e32 v0, 0
	v_mov_b32_e32 v1, 1
	s_lshl_b32 s3, s3, 8
	s_add_u32 s0, s8, s3
	s_addc_u32 s1, s9, 0
	s_add_u32 s0, s0, 0x1400
	s_addc_u32 s1, s1, 0
	global_atomic_add v4, v0, v1, s[0:1] sc0
	v_mov_b32_e32 v5, 0x23ff0
	ds_read2_b32 v[2:3], v5 offset1:1
	s_add_u32 s8, s8, 0x3400
	s_addc_u32 s9, s9, 0
	s_sub_i32 s3, 6, s90
	s_mov_b32 s7, 0
	s_waitcnt lgkmcnt(0)
	v_readfirstlane_b32 s1, v2
	v_readfirstlane_b32 s6, v3
	s_mul_i32 s1, s1, s3
	s_mul_i32 s6, s6, s3
	s_waitcnt vmcnt(0)
	v_readfirstlane_b32 s0, v4
	s_add_i32 s0, s0, 1
	s_cmp_lg_u32 s0, s1
	s_cbranch_scc1 .Lgb5_inv
	buffer_wbl2 sc1
	s_waitcnt vmcnt(0)
	global_atomic_add v0, v1, s[8:9]
.Lgb5_inv:
	buffer_inv sc1
.Lgb5_poll:
	global_load_dword v4, v0, s[8:9] sc1
	s_waitcnt vmcnt(0)
	v_readfirstlane_b32 s0, v4
	s_sub_i32 s0, s0, s6
	s_cmp_ge_i32 s0, 0
	s_cbranch_scc1 .Lgb5_rel
	s_add_i32 s7, s7, 1
	s_sleep 1
	s_cmp_lt_u32 s7, 0x2000
	s_cbranch_scc1 .Lgb5_poll

.LBB0_755:
	s_cmp_lt_i32 s91, 8
	s_cbranch_scc1 .LBB0_809
	s_waitcnt vmcnt(0)
	s_waitcnt lgkmcnt(0)
	s_barrier
	s_mov_b64 s[4:5], exec
	v_readlane_b32 s0, v126, 10
	v_readlane_b32 s1, v126, 11
	s_and_b64 s[0:1], s[4:5], s[0:1]
	s_mov_b64 exec, s[0:1]
	s_cbranch_execz .LBB0_808
	v_readlane_b32 s8, v126, 12
	v_readlane_b32 s9, v126, 13
	v_readlane_b32 s3, v126, 14
	v_mov_b32_e32 v0, 0
	v_mov_b32_e32 v1, 1
	s_lshl_b32 s3, s3, 8
	s_add_u32 s0, s8, s3
	s_addc_u32 s1, s9, 0
	s_add_u32 s0, s0, 0x1400
	s_addc_u32 s1, s1, 0
	global_atomic_add v4, v0, v1, s[0:1] sc0
	v_mov_b32_e32 v5, 0x23ff0
	ds_read2_b32 v[2:3], v5 offset1:1
	s_add_u32 s8, s8, 0x3400
	s_addc_u32 s9, s9, 0
	s_sub_i32 s3, 7, s90
	s_mov_b32 s7, 0
	s_waitcnt lgkmcnt(0)
	v_readfirstlane_b32 s1, v2
	v_readfirstlane_b32 s6, v3
	s_mul_i32 s1, s1, s3
	s_mul_i32 s6, s6, s3
	s_waitcnt vmcnt(0)
	v_readfirstlane_b32 s0, v4
	s_add_i32 s0, s0, 1
	s_cmp_lg_u32 s0, s1
	s_cbranch_scc1 .Lgb6_inv
	buffer_wbl2 sc1
	s_waitcnt vmcnt(0)
	global_atomic_add v0, v1, s[8:9]
.Lgb6_inv:
	buffer_inv sc1
.Lgb6_poll:
	global_load_dword v4, v0, s[8:9] sc1
	s_waitcnt vmcnt(0)
	v_readfirstlane_b32 s0, v4
	s_sub_i32 s0, s0, s6
	s_cmp_ge_i32 s0, 0
	s_cbranch_scc1 .Lgb6_rel
	s_add_i32 s7, s7, 1
	s_sleep 1
	s_cmp_lt_u32 s7, 0x2000
	s_cbranch_scc1 .Lgb6_poll

.LBB0_849:
	s_cmp_lt_i32 s91, 9
	s_cbranch_scc1 .LBB0_903
	s_waitcnt vmcnt(0)
	s_waitcnt lgkmcnt(0)
	s_barrier
	s_mov_b64 s[4:5], exec
	v_readlane_b32 s0, v126, 10
	v_readlane_b32 s1, v126, 11
	s_and_b64 s[0:1], s[4:5], s[0:1]
	s_mov_b64 exec, s[0:1]
	s_cbranch_execz .LBB0_902
	v_readlane_b32 s8, v126, 12
	v_readlane_b32 s9, v126, 13
	v_readlane_b32 s3, v126, 14
	v_mov_b32_e32 v0, 0
	v_mov_b32_e32 v1, 1
	s_lshl_b32 s3, s3, 8
	s_add_u32 s0, s8, s3
	s_addc_u32 s1, s9, 0
	s_add_u32 s0, s0, 0x1400
	s_addc_u32 s1, s1, 0
	global_atomic_add v4, v0, v1, s[0:1] sc0
	v_mov_b32_e32 v5, 0x23ff0
	ds_read2_b32 v[2:3], v5 offset1:1
	s_add_u32 s8, s8, 0x3400
	s_addc_u32 s9, s9, 0
	s_sub_i32 s3, 8, s90
	s_mov_b32 s7, 0
	s_waitcnt lgkmcnt(0)
	v_readfirstlane_b32 s1, v2
	v_readfirstlane_b32 s6, v3
	s_mul_i32 s1, s1, s3
	s_mul_i32 s6, s6, s3
	s_waitcnt vmcnt(0)
	v_readfirstlane_b32 s0, v4
	s_add_i32 s0, s0, 1
	s_cmp_lg_u32 s0, s1
	s_cbranch_scc1 .Lgb7_inv
	buffer_wbl2 sc1
	s_waitcnt vmcnt(0)
	global_atomic_add v0, v1, s[8:9]
.Lgb7_inv:
	buffer_inv sc1
.Lgb7_poll:
	global_load_dword v4, v0, s[8:9] sc1
	s_waitcnt vmcnt(0)
	v_readfirstlane_b32 s0, v4
	s_sub_i32 s0, s0, s6
	s_cmp_ge_i32 s0, 0
	s_cbranch_scc1 .Lgb7_rel
	s_add_i32 s7, s7, 1
	s_sleep 1
	s_cmp_lt_u32 s7, 0x2000
	s_cbranch_scc1 .Lgb7_poll

.LBB0_920:
	s_cmp_lt_i32 s91, 10
	s_cbranch_scc1 .LBB0_974
	s_waitcnt vmcnt(0)
	s_waitcnt vmcnt(0) lgkmcnt(0)
	s_barrier
	s_mov_b64 s[4:5], exec
	v_readlane_b32 s0, v126, 10
	v_readlane_b32 s1, v126, 11
	s_and_b64 s[0:1], s[4:5], s[0:1]
	s_mov_b64 exec, s[0:1]
	s_cbranch_execz .LBB0_973
	v_readlane_b32 s8, v126, 12
	v_readlane_b32 s9, v126, 13
	v_readlane_b32 s3, v126, 14
	v_mov_b32_e32 v0, 0
	v_mov_b32_e32 v1, 1
	s_lshl_b32 s3, s3, 8
	s_add_u32 s0, s8, s3
	s_addc_u32 s1, s9, 0
	s_add_u32 s0, s0, 0x1400
	s_addc_u32 s1, s1, 0
	global_atomic_add v4, v0, v1, s[0:1] sc0
	v_mov_b32_e32 v5, 0x23ff0
	ds_read2_b32 v[2:3], v5 offset1:1
	s_add_u32 s8, s8, 0x3400
	s_addc_u32 s9, s9, 0
	s_sub_i32 s3, 9, s90
	s_mov_b32 s7, 0
	s_waitcnt lgkmcnt(0)
	v_readfirstlane_b32 s1, v2
	v_readfirstlane_b32 s6, v3
	s_mul_i32 s1, s1, s3
	s_mul_i32 s6, s6, s3
	s_waitcnt vmcnt(0)
	v_readfirstlane_b32 s0, v4
	s_add_i32 s0, s0, 1
	s_cmp_lg_u32 s0, s1
	s_cbranch_scc1 .Lgb8_inv
	buffer_wbl2 sc1
	s_waitcnt vmcnt(0)
	global_atomic_add v0, v1, s[8:9]
.Lgb8_inv:
	buffer_inv sc1
.Lgb8_poll:
	global_load_dword v4, v0, s[8:9] sc1
	s_waitcnt vmcnt(0)
	v_readfirstlane_b32 s0, v4
	s_sub_i32 s0, s0, s6
	s_cmp_ge_i32 s0, 0
	s_cbranch_scc1 .Lgb8_rel
	s_add_i32 s7, s7, 1
	s_sleep 1
	s_cmp_lt_u32 s7, 0x2000
	s_cbranch_scc1 .Lgb8_poll

.LBB0_991:
	s_cmp_lt_i32 s91, 11
	s_cbranch_scc1 .LBB0_1045
	s_waitcnt vmcnt(0)
	s_waitcnt vmcnt(0) lgkmcnt(0)
	s_barrier
	s_mov_b64 s[4:5], exec
	v_readlane_b32 s0, v126, 10
	v_readlane_b32 s1, v126, 11
	s_and_b64 s[0:1], s[4:5], s[0:1]
	s_mov_b64 exec, s[0:1]
	s_cbranch_execz .LBB0_1044
	v_readlane_b32 s8, v126, 12
	v_readlane_b32 s9, v126, 13
	v_readlane_b32 s3, v126, 14
	v_mov_b32_e32 v0, 0
	v_mov_b32_e32 v1, 1
	s_lshl_b32 s3, s3, 8
	s_add_u32 s0, s8, s3
	s_addc_u32 s1, s9, 0
	s_add_u32 s0, s0, 0x1400
	s_addc_u32 s1, s1, 0
	global_atomic_add v4, v0, v1, s[0:1] sc0
	v_mov_b32_e32 v5, 0x23ff0
	ds_read2_b32 v[2:3], v5 offset1:1
	s_add_u32 s8, s8, 0x3400
	s_addc_u32 s9, s9, 0
	s_sub_i32 s3, 10, s90
	s_mov_b32 s7, 0
	s_waitcnt lgkmcnt(0)
	v_readfirstlane_b32 s1, v2
	v_readfirstlane_b32 s6, v3
	s_mul_i32 s1, s1, s3
	s_mul_i32 s6, s6, s3
	s_waitcnt vmcnt(0)
	v_readfirstlane_b32 s0, v4
	s_add_i32 s0, s0, 1
	s_cmp_lg_u32 s0, s1
	s_cbranch_scc1 .Lgb9_inv
	buffer_wbl2 sc1
	s_waitcnt vmcnt(0)
	global_atomic_add v0, v1, s[8:9]
.Lgb9_inv:
	buffer_inv sc1
.Lgb9_poll:
	global_load_dword v4, v0, s[8:9] sc1
	s_waitcnt vmcnt(0)
	v_readfirstlane_b32 s0, v4
	s_sub_i32 s0, s0, s6
	s_cmp_ge_i32 s0, 0
	s_cbranch_scc1 .Lgb9_rel
	s_add_i32 s7, s7, 1
	s_sleep 1
	s_cmp_lt_u32 s7, 0x2000
	s_cbranch_scc1 .Lgb9_poll

.LBB0_1055:
	s_or_b64 exec, exec, s[8:9]
	s_cmp_lt_i32 s91, 12
	s_cbranch_scc1 .LBB0_1109
	s_waitcnt vmcnt(0)
	s_waitcnt lgkmcnt(0)
	s_barrier
	s_mov_b64 s[4:5], exec
	v_readlane_b32 s0, v126, 10
	v_readlane_b32 s1, v126, 11
	s_and_b64 s[0:1], s[4:5], s[0:1]
	s_mov_b64 exec, s[0:1]
	s_cbranch_execz .LBB0_1108
	v_readlane_b32 s8, v126, 12
	v_readlane_b32 s9, v126, 13
	v_readlane_b32 s3, v126, 14
	v_mov_b32_e32 v0, 0
	v_mov_b32_e32 v1, 1
	s_lshl_b32 s3, s3, 8
	s_add_u32 s0, s8, s3
	s_addc_u32 s1, s9, 0
	s_add_u32 s0, s0, 0x1400
	s_addc_u32 s1, s1, 0
	global_atomic_add v4, v0, v1, s[0:1] sc0
	v_mov_b32_e32 v5, 0x23ff0
	ds_read2_b32 v[2:3], v5 offset1:1
	s_add_u32 s8, s8, 0x3400
	s_addc_u32 s9, s9, 0
	s_sub_i32 s3, 11, s90
	s_mov_b32 s7, 0
	s_waitcnt lgkmcnt(0)
	v_readfirstlane_b32 s1, v2
	v_readfirstlane_b32 s6, v3
	s_mul_i32 s1, s1, s3
	s_mul_i32 s6, s6, s3
	s_waitcnt vmcnt(0)
	v_readfirstlane_b32 s0, v4
	s_add_i32 s0, s0, 1
	s_cmp_lg_u32 s0, s1
	s_cbranch_scc1 .Lgb10_inv
	buffer_wbl2 sc1
	s_waitcnt vmcnt(0)
	global_atomic_add v0, v1, s[8:9]
.Lgb10_inv:
	buffer_inv sc1
.Lgb10_poll:
	global_load_dword v4, v0, s[8:9] sc1
	s_waitcnt vmcnt(0)
	v_readfirstlane_b32 s0, v4
	s_sub_i32 s0, s0, s6
	s_cmp_ge_i32 s0, 0
	s_cbranch_scc1 .Lgb10_rel
	s_add_i32 s7, s7, 1
	s_sleep 1
	s_cmp_lt_u32 s7, 0x2000
	s_cbranch_scc1 .Lgb10_poll

.LBB0_1153:
	s_waitcnt vmcnt(0)
	s_waitcnt vmcnt(0) lgkmcnt(0)
	s_barrier
	s_mov_b64 s[4:5], exec
	v_readlane_b32 s0, v126, 10
	v_readlane_b32 s1, v126, 11
	s_and_b64 s[0:1], s[4:5], s[0:1]
	s_mov_b64 exec, s[0:1]
	s_cbranch_execz .LBB0_1205
	v_readlane_b32 s8, v126, 12
	v_readlane_b32 s9, v126, 13
	v_readlane_b32 s3, v126, 14
	v_mov_b32_e32 v0, 0
	v_mov_b32_e32 v1, 1
	s_lshl_b32 s3, s3, 8
	s_add_u32 s0, s8, s3
	s_addc_u32 s1, s9, 0
	s_add_u32 s0, s0, 0x1400
	s_addc_u32 s1, s1, 0
	global_atomic_add v4, v0, v1, s[0:1] sc0
	v_mov_b32_e32 v5, 0x23ff0
	ds_read2_b32 v[2:3], v5 offset1:1
	s_add_u32 s8, s8, 0x3400
	s_addc_u32 s9, s9, 0
	s_sub_i32 s3, 12, s90
	s_mov_b32 s7, 0
	s_waitcnt lgkmcnt(0)
	v_readfirstlane_b32 s1, v2
	v_readfirstlane_b32 s6, v3
	s_mul_i32 s1, s1, s3
	s_mul_i32 s6, s6, s3
	s_waitcnt vmcnt(0)
	v_readfirstlane_b32 s0, v4
	s_add_i32 s0, s0, 1
	s_cmp_lg_u32 s0, s1
	s_cbranch_scc1 .Lgb11_inv
	buffer_wbl2 sc1
	s_waitcnt vmcnt(0)
	global_atomic_add v0, v1, s[8:9]
.Lgb11_inv:
	buffer_inv sc1
.Lgb11_poll:
	global_load_dword v4, v0, s[8:9] sc1
	s_waitcnt vmcnt(0)
	v_readfirstlane_b32 s0, v4
	s_sub_i32 s0, s0, s6
	s_cmp_ge_i32 s0, 0
	s_cbranch_scc1 .Lgb11_rel
	s_add_i32 s7, s7, 1
	s_sleep 1
	s_cmp_lt_u32 s7, 0x2000
	s_cbranch_scc1 .Lgb11_poll

.LBB0_1212:
	s_cmp_lt_i32 s91, 14
	s_cbranch_scc1 .LBB0_1266
	s_waitcnt vmcnt(0)
	s_waitcnt vmcnt(0) lgkmcnt(0)
	s_barrier
	s_mov_b64 s[6:7], exec
	v_readlane_b32 s0, v126, 10
	v_readlane_b32 s1, v126, 11
	s_and_b64 s[0:1], s[6:7], s[0:1]
	s_mov_b64 exec, s[0:1]
	s_cbranch_execz .LBB0_1265
	v_readlane_b32 s8, v126, 12
	v_readlane_b32 s9, v126, 13
	v_readlane_b32 s3, v126, 14
	v_mov_b32_e32 v0, 0
	v_mov_b32_e32 v1, 1
	s_lshl_b32 s3, s3, 8
	s_add_u32 s0, s8, s3
	s_addc_u32 s1, s9, 0
	s_add_u32 s0, s0, 0x1400
	s_addc_u32 s1, s1, 0
	global_atomic_add v4, v0, v1, s[0:1] sc0
	v_mov_b32_e32 v5, 0x23ff0
	ds_read2_b32 v[2:3], v5 offset1:1
	s_add_u32 s8, s8, 0x3400
	s_addc_u32 s9, s9, 0
	s_sub_i32 s3, 13, s90
	s_mov_b32 s5, 0
	s_waitcnt lgkmcnt(0)
	v_readfirstlane_b32 s1, v2
	v_readfirstlane_b32 s4, v3
	s_mul_i32 s1, s1, s3
	s_mul_i32 s4, s4, s3
	s_waitcnt vmcnt(0)
	v_readfirstlane_b32 s0, v4
	s_add_i32 s0, s0, 1
	s_cmp_lg_u32 s0, s1
	s_cbranch_scc1 .Lgb12_inv
	buffer_wbl2 sc1
	s_waitcnt vmcnt(0)
	global_atomic_add v0, v1, s[8:9]
.Lgb12_inv:
	buffer_inv sc1
.Lgb12_poll:
	global_load_dword v4, v0, s[8:9] sc1
	s_waitcnt vmcnt(0)
	v_readfirstlane_b32 s0, v4
	s_sub_i32 s0, s0, s4
	s_cmp_ge_i32 s0, 0
	s_cbranch_scc1 .Lgb12_rel
	s_add_i32 s5, s5, 1
	s_sleep 1
	s_cmp_lt_u32 s5, 0x2000
	s_cbranch_scc1 .Lgb12_poll

.LBB0_1291:
	s_cmp_lt_i32 s91, 15
	s_cbranch_scc1 .LBB0_1345
	s_waitcnt vmcnt(0)
	s_waitcnt vmcnt(0) lgkmcnt(0)
	s_barrier
	s_mov_b64 s[4:5], exec
	v_readlane_b32 s0, v126, 10
	v_readlane_b32 s1, v126, 11
	s_and_b64 s[0:1], s[4:5], s[0:1]
	s_mov_b64 exec, s[0:1]
	s_cbranch_execz .LBB0_1344
	v_readlane_b32 s8, v126, 12
	v_readlane_b32 s9, v126, 13
	v_readlane_b32 s3, v126, 14
	v_mov_b32_e32 v0, 0
	v_mov_b32_e32 v1, 1
	s_lshl_b32 s3, s3, 8
	s_add_u32 s0, s8, s3
	s_addc_u32 s1, s9, 0
	s_add_u32 s0, s0, 0x1400
	s_addc_u32 s1, s1, 0
	global_atomic_add v4, v0, v1, s[0:1] sc0
	v_mov_b32_e32 v5, 0x23ff0
	ds_read2_b32 v[2:3], v5 offset1:1
	s_add_u32 s8, s8, 0x3400
	s_addc_u32 s9, s9, 0
	s_sub_i32 s3, 14, s90
	s_mov_b32 s7, 0
	s_waitcnt lgkmcnt(0)
	v_readfirstlane_b32 s1, v2
	v_readfirstlane_b32 s6, v3
	s_mul_i32 s1, s1, s3
	s_mul_i32 s6, s6, s3
	s_waitcnt vmcnt(0)
	v_readfirstlane_b32 s0, v4
	s_add_i32 s0, s0, 1
	s_cmp_lg_u32 s0, s1
	s_cbranch_scc1 .Lgb13_inv
	buffer_wbl2 sc1
	s_waitcnt vmcnt(0)
	global_atomic_add v0, v1, s[8:9]
.Lgb13_inv:
	buffer_inv sc1
.Lgb13_poll:
	global_load_dword v4, v0, s[8:9] sc1
	s_waitcnt vmcnt(0)
	v_readfirstlane_b32 s0, v4
	s_sub_i32 s0, s0, s6
	s_cmp_ge_i32 s0, 0
	s_cbranch_scc1 .Lgb13_rel
	s_add_i32 s7, s7, 1
	s_sleep 1
	s_cmp_lt_u32 s7, 0x2000
	s_cbranch_scc1 .Lgb13_poll

.LBB0_1356:
	s_cmp_lt_i32 s91, 16
	s_cbranch_scc1 .LBB0_1410
	s_waitcnt vmcnt(0)
	s_waitcnt lgkmcnt(0)
	s_barrier
	s_mov_b64 s[4:5], exec
	v_readlane_b32 s0, v126, 10
	v_readlane_b32 s1, v126, 11
	s_and_b64 s[0:1], s[4:5], s[0:1]
	s_mov_b64 exec, s[0:1]
	s_cbranch_execz .LBB0_1409
	v_readlane_b32 s8, v126, 12
	v_readlane_b32 s9, v126, 13
	v_readlane_b32 s3, v126, 14
	v_mov_b32_e32 v0, 0
	v_mov_b32_e32 v1, 1
	s_lshl_b32 s3, s3, 8
	s_add_u32 s0, s8, s3
	s_addc_u32 s1, s9, 0
	s_add_u32 s0, s0, 0x1400
	s_addc_u32 s1, s1, 0
	global_atomic_add v4, v0, v1, s[0:1] sc0
	v_mov_b32_e32 v5, 0x23ff0
	ds_read2_b32 v[2:3], v5 offset1:1
	s_add_u32 s8, s8, 0x3400
	s_addc_u32 s9, s9, 0
	s_sub_i32 s3, 15, s90
	s_mov_b32 s7, 0
	s_waitcnt lgkmcnt(0)
	v_readfirstlane_b32 s1, v2
	v_readfirstlane_b32 s6, v3
	s_mul_i32 s1, s1, s3
	s_mul_i32 s6, s6, s3
	s_waitcnt vmcnt(0)
	v_readfirstlane_b32 s0, v4
	s_add_i32 s0, s0, 1
	s_cmp_lg_u32 s0, s1
	s_cbranch_scc1 .Lgb14_inv
	buffer_wbl2 sc1
	s_waitcnt vmcnt(0)
	global_atomic_add v0, v1, s[8:9]
.Lgb14_inv:
	buffer_inv sc1
.Lgb14_poll:
	global_load_dword v4, v0, s[8:9] sc1
	s_waitcnt vmcnt(0)
	v_readfirstlane_b32 s0, v4
	s_sub_i32 s0, s0, s6
	s_cmp_ge_i32 s0, 0
	s_cbranch_scc1 .Lgb14_rel
	s_add_i32 s7, s7, 1
	s_sleep 1
	s_cmp_lt_u32 s7, 0x2000
	s_cbranch_scc1 .Lgb14_poll

.LBB0_1450:
	s_cmp_lt_i32 s91, 17
	s_cbranch_scc1 .LBB0_1504
	s_waitcnt vmcnt(0)
	s_waitcnt vmcnt(0) lgkmcnt(0)
	s_barrier
	s_mov_b64 s[4:5], exec
	v_readlane_b32 s0, v126, 10
	v_readlane_b32 s1, v126, 11
	s_and_b64 s[0:1], s[4:5], s[0:1]
	s_mov_b64 exec, s[0:1]
	s_cbranch_execz .LBB0_1503
	v_readlane_b32 s8, v126, 12
	v_readlane_b32 s9, v126, 13
	v_readlane_b32 s3, v126, 14
	v_mov_b32_e32 v0, 0
	v_mov_b32_e32 v1, 1
	s_lshl_b32 s3, s3, 8
	s_add_u32 s0, s8, s3
	s_addc_u32 s1, s9, 0
	s_add_u32 s0, s0, 0x1400
	s_addc_u32 s1, s1, 0
	global_atomic_add v4, v0, v1, s[0:1] sc0
	v_mov_b32_e32 v5, 0x23ff0
	ds_read2_b32 v[2:3], v5 offset1:1
	s_add_u32 s8, s8, 0x3400
	s_addc_u32 s9, s9, 0
	s_sub_i32 s3, 16, s90
	s_mov_b32 s7, 0
	s_waitcnt lgkmcnt(0)
	v_readfirstlane_b32 s1, v2
	v_readfirstlane_b32 s6, v3
	s_mul_i32 s1, s1, s3
	s_mul_i32 s6, s6, s3
	s_waitcnt vmcnt(0)
	v_readfirstlane_b32 s0, v4
	s_add_i32 s0, s0, 1
	s_cmp_lg_u32 s0, s1
	s_cbranch_scc1 .Lgb15_inv
	buffer_wbl2 sc1
	s_waitcnt vmcnt(0)
	global_atomic_add v0, v1, s[8:9]
.Lgb15_inv:
	buffer_inv sc1
.Lgb15_poll:
	global_load_dword v4, v0, s[8:9] sc1
	s_waitcnt vmcnt(0)
	v_readfirstlane_b32 s0, v4
	s_sub_i32 s0, s0, s6
	s_cmp_ge_i32 s0, 0
	s_cbranch_scc1 .Lgb15_rel
	s_add_i32 s7, s7, 1
	s_sleep 1
	s_cmp_lt_u32 s7, 0x2000
	s_cbranch_scc1 .Lgb15_poll

.LBB0_1521:
	s_cmp_lt_i32 s91, 18
	s_cbranch_scc1 .LBB0_1575
	s_waitcnt vmcnt(0)
	s_waitcnt vmcnt(0) lgkmcnt(0)
	s_barrier
	s_mov_b64 s[4:5], exec
	v_readlane_b32 s0, v126, 10
	v_readlane_b32 s1, v126, 11
	s_and_b64 s[0:1], s[4:5], s[0:1]
	s_mov_b64 exec, s[0:1]
	s_cbranch_execz .LBB0_1574
	v_readlane_b32 s8, v126, 12
	v_readlane_b32 s9, v126, 13
	v_readlane_b32 s3, v126, 14
	v_mov_b32_e32 v0, 0
	v_mov_b32_e32 v1, 1
	s_lshl_b32 s3, s3, 8
	s_add_u32 s0, s8, s3
	s_addc_u32 s1, s9, 0
	s_add_u32 s0, s0, 0x1400
	s_addc_u32 s1, s1, 0
	global_atomic_add v4, v0, v1, s[0:1] sc0
	v_mov_b32_e32 v5, 0x23ff0
	ds_read2_b32 v[2:3], v5 offset1:1
	s_add_u32 s8, s8, 0x3400
	s_addc_u32 s9, s9, 0
	s_sub_i32 s3, 17, s90
	s_mov_b32 s7, 0
	s_waitcnt lgkmcnt(0)
	v_readfirstlane_b32 s1, v2
	v_readfirstlane_b32 s6, v3
	s_mul_i32 s1, s1, s3
	s_mul_i32 s6, s6, s3
	s_waitcnt vmcnt(0)
	v_readfirstlane_b32 s0, v4
	s_add_i32 s0, s0, 1
	s_cmp_lg_u32 s0, s1
	s_cbranch_scc1 .Lgb16_inv
	buffer_wbl2 sc1
	s_waitcnt vmcnt(0)
	global_atomic_add v0, v1, s[8:9]
.Lgb16_inv:
	buffer_inv sc1
.Lgb16_poll:
	global_load_dword v4, v0, s[8:9] sc1
	s_waitcnt vmcnt(0)
	v_readfirstlane_b32 s0, v4
	s_sub_i32 s0, s0, s6
	s_cmp_ge_i32 s0, 0
	s_cbranch_scc1 .Lgb16_rel
	s_add_i32 s7, s7, 1
	s_sleep 1
	s_cmp_lt_u32 s7, 0x2000
	s_cbranch_scc1 .Lgb16_poll

.LBB0_1592:
	s_cmp_lt_i32 s91, 19
	s_cbranch_scc1 .LBB0_1646
	s_waitcnt vmcnt(0)
	s_waitcnt vmcnt(0) lgkmcnt(0)
	s_barrier
	s_mov_b64 s[4:5], exec
	v_readlane_b32 s0, v126, 10
	v_readlane_b32 s1, v126, 11
	s_and_b64 s[0:1], s[4:5], s[0:1]
	s_mov_b64 exec, s[0:1]
	s_cbranch_execz .LBB0_1645
	v_readlane_b32 s8, v126, 12
	v_readlane_b32 s9, v126, 13
	v_readlane_b32 s3, v126, 14
	v_mov_b32_e32 v0, 0
	v_mov_b32_e32 v1, 1
	s_lshl_b32 s3, s3, 8
	s_add_u32 s0, s8, s3
	s_addc_u32 s1, s9, 0
	s_add_u32 s0, s0, 0x1400
	s_addc_u32 s1, s1, 0
	global_atomic_add v4, v0, v1, s[0:1] sc0
	v_mov_b32_e32 v5, 0x23ff0
	ds_read2_b32 v[2:3], v5 offset1:1
	s_add_u32 s8, s8, 0x3400
	s_addc_u32 s9, s9, 0
	s_sub_i32 s3, 18, s90
	s_mov_b32 s7, 0
	s_waitcnt lgkmcnt(0)
	v_readfirstlane_b32 s1, v2
	v_readfirstlane_b32 s6, v3
	s_mul_i32 s1, s1, s3
	s_mul_i32 s6, s6, s3
	s_waitcnt vmcnt(0)
	v_readfirstlane_b32 s0, v4
	s_add_i32 s0, s0, 1
	s_cmp_lg_u32 s0, s1
	s_cbranch_scc1 .Lgb17_inv
	buffer_wbl2 sc1
	s_waitcnt vmcnt(0)
	global_atomic_add v0, v1, s[8:9]
.Lgb17_inv:
	buffer_inv sc1
.Lgb17_poll:
	global_load_dword v4, v0, s[8:9] sc1
	s_waitcnt vmcnt(0)
	v_readfirstlane_b32 s0, v4
	s_sub_i32 s0, s0, s6
	s_cmp_ge_i32 s0, 0
	s_cbranch_scc1 .Lgb17_rel
	s_add_i32 s7, s7, 1
	s_sleep 1
	s_cmp_lt_u32 s7, 0x2000
	s_cbranch_scc1 .Lgb17_poll
